# diff-attention loop: staggered half-step barrier for waves 4-7 plus K/V tile loads addressed as SGPR base + lane offset (no 64-bit VALU adds in the loop)
# speedup vs baseline: 1.0066x; 1.0066x over previous
; #define ATT_LAS __attribute__((address_space(3)))
; __device__ __forceinline__ int kperm(int r) { return (r & 19) | ((r & 4) << 1) | ((r & 8) >> 1); }
; __device__ __forceinline__ void diff_unit(ATT_LAS unsigned char* lds, int b, int h, int qb, const bf16_t* __restrict__ DQ, const bf16_t* __restrict__ DK, const bf16_t* __restrict__ VT,
;                                           float lam, const float* __restrict__ gout, bf16_t* __restrict__ MIXED) {
;     ...
;     bf16x8 qf[4];
; #pragma unroll
;     for (int s = 0; s < 4; ++s) qf[s] = *(const bf16x8*)(DQ + (size_t)(b * 4096 + tq) * 1024 + h * 128 + comp * 64 + 16 * s + 8 * hh);
;     f32x16 O[4], S;
; #pragma unroll
;     for (int e = 0; e < 4; ++e)
; #pragma unroll
;         for (int i = 0; i < 16; ++i) O[e][i] = 0.f;
; #pragma unroll
;     for (int i = 0; i < 16; ++i) S[i] = 0.f;
;     bf16x8 pf[2]; pf[0] = qf[0]; pf[1] = qf[0];
;     float lsum = 0.f;
;     u32x4 kr[2], vr[2];
; #pragma unroll
;     for (int t = 0; t < 2; ++t) {
; #pragma unroll
;         for (int u = 0; u < 2; ++u) { kr[u] = *(const u32x4*)(KG(u) + (size_t)t * 64 * 1024); vr[u] = *(const u32x4*)(VG(u) + t * 64); }
; #pragma unroll
;         for (int u = 0; u < 2; ++u) { *(ATT_LAS u32x4*)(lds + t * BUF_BYTES + KL(u)) = kr[u]; *(ATT_LAS u32x4*)(lds + t * BUF_BYTES + VL(u)) = vr[u]; }
;     }
; #pragma unroll
;     for (int u = 0; u < 2; ++u) { kr[u] = *(const u32x4*)(KG(u) + (size_t)2 * 64 * 1024); vr[u] = *(const u32x4*)(VG(u) + 2 * 64); }
;     __syncthreads();
;     const int koff = kperm(r) * KPITCH + (64 * comp + 8 * hh) * 2, voff = KS_BYTES + r * VPITCH + 8 * hh * 2;
;     ...
;     int n = 0;
.LBB0_535:
	s_lshl_b32 s22, s46, 1
	s_add_i32 s23, s22, 3
	s_cmp_lt_u32 s42, 3
	s_cbranch_scc1 .LBB0_542
	v_mov_b32_e32 v16, 0
	s_add_i32 s24, s45, s39
	s_movk_i32 s25, 0x1c0
	s_mov_b32 s46, 0
	s_movk_i32 s47, 0x60
	v_mov_b32_e32 v17, v16
	v_mov_b32_e32 v18, v16
	v_mov_b32_e32 v19, v16
	v_mov_b32_e32 v20, v16
	v_mov_b32_e32 v21, v16
	v_mov_b32_e32 v22, v16
	v_mov_b32_e32 v23, v16
	v_mov_b32_e32 v24, v16
	v_mov_b32_e32 v25, v16
	v_mov_b32_e32 v26, v16
	v_mov_b32_e32 v27, v16
	v_mov_b32_e32 v28, v16
	v_mov_b32_e32 v29, v16
	v_mov_b32_e32 v30, v16
	v_mov_b32_e32 v31, v16
	v_mov_b32_e32 v32, v16
	v_mov_b32_e32 v33, v16
	v_mov_b32_e32 v34, v16
	v_mov_b32_e32 v35, v16
	v_mov_b32_e32 v36, v16
	v_mov_b32_e32 v37, v16
	v_mov_b32_e32 v38, v16
	v_mov_b32_e32 v39, v16
	v_mov_b32_e32 v40, v16
	v_mov_b32_e32 v41, v16
	v_mov_b32_e32 v42, v16
	v_mov_b32_e32 v43, v16
	v_mov_b32_e32 v44, v16
	v_mov_b32_e32 v45, v16
	v_mov_b32_e32 v46, v16
	v_mov_b32_e32 v47, v16
	v_mov_b32_e32 v48, v16
	v_mov_b32_e32 v49, v16
	v_mov_b32_e32 v50, v16
	v_mov_b32_e32 v51, v16
	v_mov_b32_e32 v52, v16
	v_mov_b32_e32 v53, v16
	v_mov_b32_e32 v54, v16
	v_mov_b32_e32 v55, v16
	v_mov_b32_e32 v56, v16
	v_mov_b32_e32 v57, v16
	v_mov_b32_e32 v58, v16
	v_mov_b32_e32 v59, v16
	v_mov_b32_e32 v60, v16
	v_mov_b32_e32 v61, v16
	v_mov_b32_e32 v62, v16
	v_mov_b32_e32 v63, v16
	v_mov_b32_e32 v64, v16
	v_mov_b32_e32 v65, v16
	v_mov_b32_e32 v66, v16
	v_mov_b32_e32 v67, v16
	v_mov_b32_e32 v68, v16
	v_mov_b32_e32 v69, v16
	v_mov_b32_e32 v70, v16
	v_mov_b32_e32 v71, v16
	v_mov_b32_e32 v72, v16
	v_mov_b32_e32 v73, v16
	v_mov_b32_e32 v74, v16
	v_mov_b32_e32 v75, v16
	v_mov_b32_e32 v76, v16
	v_mov_b32_e32 v77, v16
	v_mov_b32_e32 v78, v16
	v_mov_b32_e32 v79, v16
	s_mov_b32 s98, 0
	s_mov_b32 s99, 0x8c00
	s_mov_b32 s100, 0x11800
	s_mov_b32 s47, 4
	v_mov_b32_e32 v150, v148
	v_subrev_u32_e32 v240, s20, v182
	v_add_u32_e32 v241, 0x10000, v240
	v_subrev_u32_e32 v242, s12, v184
	v_add_u32_e32 v243, 0x208000, v242
	v_mov_b32_e32 v151, v149
	v_add_u32_e32 v14, 0x8c00, v163
	v_mov_b32_e32 v1, v196
	ds_read_b128 v[218:221], v14 offset:8704
	ds_read_b128 v[222:225], v1 offset:17472
	ds_read_b128 v[226:229], v14 offset:8736
	ds_read_b128 v[230:233], v1 offset:22080
	ds_read_b128 v[234:237], v14 offset:8768
	ds_read_b128 v[2:5], v1 offset:26688
	s_waitcnt lgkmcnt(0)
; #define ATT_LAS __attribute__((address_space(3)))
; #define SB0() __builtin_amdgcn_sched_barrier(0)
; __device__ __forceinline__ void hs_fast(f32x16& S, f32x16 (&O)[4], bf16x8 (&pf)[2], float& lsum, const bf16x8 (&qf)[4], const ATT_LAS unsigned char* ka, const ATT_LAS unsigned char* va) {
;     bf16x8 kf[4], vf[8]; f32x16 N; float acc;
;     const f32x16 Z = {0.f, 0.f, 0.f, 0.f, 0.f, 0.f, 0.f, 0.f, 0.f, 0.f, 0.f, 0.f, 0.f, 0.f, 0.f, 0.f};
;     kf[0] = LDF(ka); kf[1] = LDF(ka + 32); kf[2] = LDF(ka + 64); kf[3] = LDF(ka + 96);
;     vf[0] = LDF(va); vf[1] = LDF(va + 32 * VPITCH); vf[2] = LDF(va + 64 * VPITCH); vf[3] = LDF(va + 96 * VPITCH);
;     SB0();
;     N = MFMA32(kf[0], qf[0], Z);          S[0] = EX2(S[0]); S[1] = EX2(S[1]);
;     SB0();
;     O[0] = MFMA32(vf[0], pf[0], O[0]);    S[2] = EX2(S[2]); S[3] = EX2(S[3]); acc = S[0] + S[1];
;     SB0();
;     N = MFMA32(kf[1], qf[1], N);          S[4] = EX2(S[4]); S[5] = EX2(S[5]); acc += S[2]; acc += S[3];
;     SB0();
;     O[1] = MFMA32(vf[1], pf[0], O[1]);    S[6] = EX2(S[6]); S[7] = EX2(S[7]); acc += S[4]; acc += S[5];
;     SB0();
;     N = MFMA32(kf[2], qf[2], N);          S[8] = EX2(S[8]); S[9] = EX2(S[9]); acc += S[6]; acc += S[7];
;     vf[4] = LDF(va + 32); vf[5] = LDF(va + 32 * VPITCH + 32);
;     SB0();
;     O[2] = MFMA32(vf[2], pf[0], O[2]);    S[10] = EX2(S[10]); S[11] = EX2(S[11]); acc += S[8]; acc += S[9];
;     vf[6] = LDF(va + 64 * VPITCH + 32); vf[7] = LDF(va + 96 * VPITCH + 32);
;     SB0();
;     N = MFMA32(kf[3], qf[3], N);          S[12] = EX2(S[12]); S[13] = EX2(S[13]); acc += S[10]; acc += S[11];
;     SB0();
;     O[3] = MFMA32(vf[3], pf[0], O[3]);    S[14] = EX2(S[14]); S[15] = EX2(S[15]); acc += S[12]; acc += S[13];
;     SB0();
;     u32x4 w0, w1;
;     O[0] = MFMA32(vf[4], pf[1], O[0]);    w0.x = cvt_pk_bf16(S[0], S[1]); w0.y = cvt_pk_bf16(S[2], S[3]); acc += S[14]; acc += S[15];
;     SB0();
;     O[1] = MFMA32(vf[5], pf[1], O[1]);    w0.z = cvt_pk_bf16(S[4], S[5]); w0.w = cvt_pk_bf16(S[6], S[7]);
;     SB0();
;     O[2] = MFMA32(vf[6], pf[1], O[2]);    w1.x = cvt_pk_bf16(S[8], S[9]); w1.y = cvt_pk_bf16(S[10], S[11]);
;     SB0();
;     O[3] = MFMA32(vf[7], pf[1], O[3]);    w1.z = cvt_pk_bf16(S[12], S[13]); w1.w = cvt_pk_bf16(S[14], S[15]);
;     SB0();
;     lsum += acc; pf[0] = __builtin_bit_cast(bf16x8, w0); pf[1] = __builtin_bit_cast(bf16x8, w1); S = N;
; }
.Lfa_even:
	v_mov_b32_e32 v15, v1
	v_add_u32_e32 v1, s99, v196
	s_waitcnt lgkmcnt(9)
	v_mfma_f32_32x32x16_bf16 v[96:111], v[218:221], v[112:115], 0
	v_exp_f32_e32 v80, v80
	v_exp_f32_e32 v81, v81
	ds_read_b128 v[218:221], v14 offset:8800
	v_add_f32_e32 v244, v80, v81
	s_waitcnt lgkmcnt(8)
	v_mfma_f32_32x32x16_bf16 v[64:79], v[222:225], v[144:147], v[64:79]
	v_exp_f32_e32 v82, v82
	v_exp_f32_e32 v83, v83
	ds_read_b128 v[222:225], v15 offset:31296
	v_add_f32_e32 v245, v82, v83
	s_waitcnt lgkmcnt(7)
	v_mfma_f32_32x32x16_bf16 v[96:111], v[226:229], v[116:119], v[96:111]
	v_exp_f32_e32 v84, v84
	v_exp_f32_e32 v85, v85
	ds_read_b128 v[226:229], v15 offset:17504
	v_add_f32_e32 v244, v244, v84
	v_add_f32_e32 v245, v245, v85
	s_waitcnt lgkmcnt(6)
	v_mfma_f32_32x32x16_bf16 v[48:63], v[230:233], v[144:147], v[48:63]
	v_exp_f32_e32 v86, v86
	v_exp_f32_e32 v87, v87
	ds_read_b128 v[230:233], v15 offset:22112
	v_add_f32_e32 v244, v244, v86
	v_add_f32_e32 v245, v245, v87
	s_waitcnt lgkmcnt(5)
	v_mfma_f32_32x32x16_bf16 v[96:111], v[234:237], v[120:123], v[96:111]
	v_exp_f32_e32 v88, v88
	v_exp_f32_e32 v89, v89
	ds_read_b128 v[234:237], v15 offset:26720
	v_add_f32_e32 v244, v244, v88
	v_add_f32_e32 v245, v245, v89
	s_waitcnt lgkmcnt(5)
	v_mfma_f32_32x32x16_bf16 v[32:47], v[2:5], v[144:147], v[32:47]
	v_exp_f32_e32 v90, v90
	v_exp_f32_e32 v91, v91
	ds_read_b128 v[2:5], v15 offset:31328
	v_add_f32_e32 v244, v244, v90
	v_add_f32_e32 v245, v245, v91
	s_waitcnt lgkmcnt(5)
	v_mfma_f32_32x32x16_bf16 v[96:111], v[218:221], v[124:127], v[96:111]
	v_exp_f32_e32 v92, v92
	v_exp_f32_e32 v93, v93
	ds_read_b128 v[218:221], v1 offset:17408
	v_add_f32_e32 v244, v244, v92
	v_add_f32_e32 v245, v245, v93
	s_waitcnt lgkmcnt(5)
	v_mfma_f32_32x32x16_bf16 v[16:31], v[222:225], v[144:147], v[16:31]
	v_exp_f32_e32 v94, v94
	v_exp_f32_e32 v95, v95
	ds_read_b128 v[222:225], v1 offset:22016
	v_add_f32_e32 v244, v244, v94
	v_add_f32_e32 v245, v245, v95
	s_waitcnt lgkmcnt(5)
	v_mfma_f32_32x32x16_bf16 v[64:79], v[226:229], v[150:153], v[64:79]
	v_add_f32_e32 v161, v161, v244
	v_cvt_pk_bf16_f32 v6, v80, v81
	v_cvt_pk_bf16_f32 v7, v82, v83
	ds_read_b128 v[226:229], v1 offset:26624
	s_waitcnt lgkmcnt(5)
	v_mfma_f32_32x32x16_bf16 v[48:63], v[230:233], v[150:153], v[48:63]
	v_add_f32_e32 v161, v161, v245
	v_cvt_pk_bf16_f32 v8, v84, v85
	v_cvt_pk_bf16_f32 v9, v86, v87
	ds_read_b128 v[230:233], v1 offset:31232
	s_waitcnt lgkmcnt(5)
	v_mfma_f32_32x32x16_bf16 v[32:47], v[234:237], v[150:153], v[32:47]
	v_cvt_pk_bf16_f32 v10, v88, v89
	v_cvt_pk_bf16_f32 v11, v90, v91
	s_waitcnt lgkmcnt(4)
	v_mfma_f32_32x32x16_bf16 v[16:31], v[2:5], v[150:153], v[16:31]
	v_cvt_pk_bf16_f32 v12, v92, v93
	v_cvt_pk_bf16_f32 v13, v94, v95
	ds_read_b128 v[2:5], v1 offset:17440
	s_add_i32 s46, s46, 1
	s_cmp_eq_u32 s46, s24
	s_cbranch_scc1 .Lfa_exit_even
	s_cmp_eq_u32 s41, 0
	s_cbranch_scc0 .Lfa_odd_b
	s_barrier
	v_add_u32_e32 v14, s100, v163
	ds_read_b128 v[234:237], v14
	v_add_u32_e32 v246, s98, v193
	v_add_u32_e32 v247, s98, v194
	s_waitcnt lgkmcnt(5)
	v_mfma_f32_32x32x16_bf16 v[64:79], v[218:221], v[6:9], v[64:79]
	v_exp_f32_e32 v96, v96
	v_exp_f32_e32 v97, v97
	ds_read_b128 v[218:221], v14 offset:32
	v_add_f32_e32 v244, v96, v97
	s_waitcnt lgkmcnt(5)
	v_mfma_f32_32x32x16_bf16 v[48:63], v[222:225], v[6:9], v[48:63]
	v_exp_f32_e32 v98, v98
	v_exp_f32_e32 v99, v99
	ds_read_b128 v[222:225], v1 offset:22048
	v_add_f32_e32 v245, v98, v99
	s_waitcnt lgkmcnt(5)
	v_mfma_f32_32x32x16_bf16 v[32:47], v[226:229], v[6:9], v[32:47]
	v_exp_f32_e32 v100, v100
	v_exp_f32_e32 v101, v101
	ds_read_b128 v[226:229], v14 offset:64
	v_add_f32_e32 v244, v244, v100
	v_add_f32_e32 v245, v245, v101
	s_waitcnt lgkmcnt(5)
	v_mfma_f32_32x32x16_bf16 v[16:31], v[230:233], v[6:9], v[16:31]
	v_exp_f32_e32 v102, v102
	v_exp_f32_e32 v103, v103
	ds_read_b128 v[230:233], v1 offset:26656
	v_add_f32_e32 v244, v244, v102
	v_add_f32_e32 v245, v245, v103
	s_waitcnt lgkmcnt(4)
	v_mfma_f32_32x32x16_bf16 v[80:95], v[234:237], v[112:115], 0
	v_exp_f32_e32 v104, v104
	v_exp_f32_e32 v105, v105
	ds_read_b128 v[234:237], v14 offset:96
	v_add_f32_e32 v244, v244, v104
	v_add_f32_e32 v245, v245, v105
	s_waitcnt lgkmcnt(5)
	v_mfma_f32_32x32x16_bf16 v[64:79], v[2:5], v[10:13], v[64:79]
	v_exp_f32_e32 v106, v106
	v_exp_f32_e32 v107, v107
	ds_read_b128 v[2:5], v1 offset:31264
	v_add_f32_e32 v244, v244, v106
	v_add_f32_e32 v245, v245, v107
	s_waitcnt lgkmcnt(5)
	v_mfma_f32_32x32x16_bf16 v[80:95], v[218:221], v[116:119], v[80:95]
	v_exp_f32_e32 v108, v108
	v_exp_f32_e32 v109, v109
	ds_read_b128 v[218:221], v14 offset:8704
	v_add_f32_e32 v244, v244, v108
	v_add_f32_e32 v245, v245, v109
	s_waitcnt vmcnt(0)
	ds_write_b128 v246, v[128:131]
	s_waitcnt lgkmcnt(6)
	v_mfma_f32_32x32x16_bf16 v[48:63], v[222:225], v[10:13], v[48:63]
	v_exp_f32_e32 v110, v110
	v_exp_f32_e32 v111, v111
	ds_read_b128 v[222:225], v1 offset:17472
	v_add_f32_e32 v244, v244, v110
	v_add_f32_e32 v245, v245, v111
	ds_write_b128 v247, v[132:135] offset:17408
	s_waitcnt lgkmcnt(7)
	v_mfma_f32_32x32x16_bf16 v[80:95], v[226:229], v[120:123], v[80:95]
	v_add_f32_e32 v161, v161, v244
	v_cvt_pk_bf16_f32 v144, v96, v97
	v_cvt_pk_bf16_f32 v145, v98, v99
	ds_read_b128 v[226:229], v14 offset:8736
	ds_write_b128 v246, v[136:139] offset:8704
	s_waitcnt lgkmcnt(8)
	v_mfma_f32_32x32x16_bf16 v[32:47], v[230:233], v[10:13], v[32:47]
	v_add_f32_e32 v161, v161, v245
	v_cvt_pk_bf16_f32 v146, v100, v101
	v_cvt_pk_bf16_f32 v147, v102, v103
	ds_read_b128 v[230:233], v1 offset:22080
	ds_write_b128 v247, v[140:143] offset:26624
	s_waitcnt lgkmcnt(9)
	v_mfma_f32_32x32x16_bf16 v[80:95], v[234:237], v[124:127], v[80:95]
	v_cvt_pk_bf16_f32 v150, v104, v105
	v_cvt_pk_bf16_f32 v151, v106, v107
	ds_read_b128 v[234:237], v14 offset:8768
	s_cmp_ge_u32 s47, s23
	s_cbranch_scc1 .Lfa_noload
	s_lshl_b32 s48, s47, 17
	s_lshl_b32 s4, s47, 7
	s_add_u32 s48, s20, s48
	s_addc_u32 s49, s21, 0
	global_load_dwordx4 v[128:131], v240, s[48:49]
	s_add_u32 s4, s12, s4
	s_addc_u32 s25, s13, 0
	s_mov_b32 s5, s25
	global_load_dwordx4 v[132:135], v242, s[4:5]
	global_load_dwordx4 v[136:139], v241, s[48:49]
	global_load_dwordx4 v[140:143], v243, s[4:5]
	s_mov_b32 s5, 0

; #define ATT_LAS __attribute__((address_space(3)))
; #define SB0() __builtin_amdgcn_sched_barrier(0)
; __device__ __forceinline__ void hs_fast(f32x16& S, f32x16 (&O)[4], bf16x8 (&pf)[2], float& lsum, const bf16x8 (&qf)[4], const ATT_LAS unsigned char* ka, const ATT_LAS unsigned char* va) {
;     bf16x8 kf[4], vf[8]; f32x16 N; float acc;
;     const f32x16 Z = {0.f, 0.f, 0.f, 0.f, 0.f, 0.f, 0.f, 0.f, 0.f, 0.f, 0.f, 0.f, 0.f, 0.f, 0.f, 0.f};
;     kf[0] = LDF(ka); kf[1] = LDF(ka + 32); kf[2] = LDF(ka + 64); kf[3] = LDF(ka + 96);
;     vf[0] = LDF(va); vf[1] = LDF(va + 32 * VPITCH); vf[2] = LDF(va + 64 * VPITCH); vf[3] = LDF(va + 96 * VPITCH);
;     SB0();
;     N = MFMA32(kf[0], qf[0], Z);          S[0] = EX2(S[0]); S[1] = EX2(S[1]);
;     SB0();
;     O[0] = MFMA32(vf[0], pf[0], O[0]);    S[2] = EX2(S[2]); S[3] = EX2(S[3]); acc = S[0] + S[1];
;     SB0();
;     N = MFMA32(kf[1], qf[1], N);          S[4] = EX2(S[4]); S[5] = EX2(S[5]); acc += S[2]; acc += S[3];
;     SB0();
;     O[1] = MFMA32(vf[1], pf[0], O[1]);    S[6] = EX2(S[6]); S[7] = EX2(S[7]); acc += S[4]; acc += S[5];
;     SB0();
;     N = MFMA32(kf[2], qf[2], N);          S[8] = EX2(S[8]); S[9] = EX2(S[9]); acc += S[6]; acc += S[7];
;     vf[4] = LDF(va + 32); vf[5] = LDF(va + 32 * VPITCH + 32);
;     SB0();
;     O[2] = MFMA32(vf[2], pf[0], O[2]);    S[10] = EX2(S[10]); S[11] = EX2(S[11]); acc += S[8]; acc += S[9];
;     vf[6] = LDF(va + 64 * VPITCH + 32); vf[7] = LDF(va + 96 * VPITCH + 32);
;     SB0();
;     N = MFMA32(kf[3], qf[3], N);          S[12] = EX2(S[12]); S[13] = EX2(S[13]); acc += S[10]; acc += S[11];
;     SB0();
;     O[3] = MFMA32(vf[3], pf[0], O[3]);    S[14] = EX2(S[14]); S[15] = EX2(S[15]); acc += S[12]; acc += S[13];
;     SB0();
;     u32x4 w0, w1;
;     O[0] = MFMA32(vf[4], pf[1], O[0]);    w0.x = cvt_pk_bf16(S[0], S[1]); w0.y = cvt_pk_bf16(S[2], S[3]); acc += S[14]; acc += S[15];
;     SB0();
;     O[1] = MFMA32(vf[5], pf[1], O[1]);    w0.z = cvt_pk_bf16(S[4], S[5]); w0.w = cvt_pk_bf16(S[6], S[7]);
;     SB0();
;     O[2] = MFMA32(vf[6], pf[1], O[2]);    w1.x = cvt_pk_bf16(S[8], S[9]); w1.y = cvt_pk_bf16(S[10], S[11]);
;     SB0();
;     O[3] = MFMA32(vf[7], pf[1], O[3]);    w1.z = cvt_pk_bf16(S[12], S[13]); w1.w = cvt_pk_bf16(S[14], S[15]);
;     SB0();
;     lsum += acc; pf[0] = __builtin_bit_cast(bf16x8, w0); pf[1] = __builtin_bit_cast(bf16x8, w1); S = N;
; }
.Lfa_odd_b:
	s_waitcnt lgkmcnt(4)
	v_mfma_f32_32x32x16_bf16 v[64:79], v[218:221], v[6:9], v[64:79]
	v_exp_f32_e32 v96, v96
	v_exp_f32_e32 v97, v97
	ds_read_b128 v[218:221], v1 offset:22048
	v_add_f32_e32 v244, v96, v97
	s_waitcnt lgkmcnt(4)
	v_mfma_f32_32x32x16_bf16 v[48:63], v[222:225], v[6:9], v[48:63]
	v_exp_f32_e32 v98, v98
	v_exp_f32_e32 v99, v99
	ds_read_b128 v[222:225], v1 offset:26656
	v_add_f32_e32 v245, v98, v99
	s_waitcnt lgkmcnt(4)
	v_mfma_f32_32x32x16_bf16 v[32:47], v[226:229], v[6:9], v[32:47]
	v_exp_f32_e32 v100, v100
	v_exp_f32_e32 v101, v101
	ds_read_b128 v[226:229], v1 offset:31264
	v_add_f32_e32 v244, v244, v100
	v_add_f32_e32 v245, v245, v101
	s_waitcnt lgkmcnt(4)
	v_mfma_f32_32x32x16_bf16 v[16:31], v[230:233], v[6:9], v[16:31]
	v_exp_f32_e32 v102, v102
	v_exp_f32_e32 v103, v103
	v_add_f32_e32 v244, v244, v102
	v_add_f32_e32 v245, v245, v103
	s_waitcnt lgkmcnt(3)
	v_mfma_f32_32x32x16_bf16 v[64:79], v[2:5], v[10:13], v[64:79]
	v_exp_f32_e32 v104, v104
	v_exp_f32_e32 v105, v105
	v_add_f32_e32 v244, v244, v104
	v_add_f32_e32 v245, v245, v105
	s_barrier
	v_add_u32_e32 v14, s100, v163
	ds_read_b128 v[230:233], v14
	ds_read_b128 v[234:237], v14 offset:32
	ds_read_b128 v[2:5], v14 offset:64
	ds_read_b128 v[248:251], v14 offset:96
	v_add_u32_e32 v246, s98, v193
	v_add_u32_e32 v247, s98, v194
	s_waitcnt lgkmcnt(6)
	v_mfma_f32_32x32x16_bf16 v[48:63], v[218:221], v[10:13], v[48:63]
	v_exp_f32_e32 v106, v106
	v_exp_f32_e32 v107, v107
	ds_read_b128 v[218:221], v14 offset:8704
	v_add_f32_e32 v244, v244, v106
	v_add_f32_e32 v245, v245, v107
	s_waitcnt lgkmcnt(6)
	v_mfma_f32_32x32x16_bf16 v[32:47], v[222:225], v[10:13], v[32:47]
	v_exp_f32_e32 v108, v108
	v_exp_f32_e32 v109, v109
	ds_read_b128 v[222:225], v1 offset:17472
	v_add_f32_e32 v244, v244, v108
	v_add_f32_e32 v245, v245, v109
	s_waitcnt lgkmcnt(6)
	v_mfma_f32_32x32x16_bf16 v[16:31], v[226:229], v[10:13], v[16:31]
	v_exp_f32_e32 v110, v110
	v_exp_f32_e32 v111, v111
	ds_read_b128 v[226:229], v14 offset:8736
	v_add_f32_e32 v244, v244, v110
	v_add_f32_e32 v245, v245, v111
	s_waitcnt vmcnt(0)
	ds_write_b128 v246, v[128:131]
	s_waitcnt lgkmcnt(7)
	v_mfma_f32_32x32x16_bf16 v[80:95], v[230:233], v[112:115], 0
	v_add_f32_e32 v161, v161, v244
	v_cvt_pk_bf16_f32 v144, v96, v97
	v_cvt_pk_bf16_f32 v145, v98, v99
	ds_read_b128 v[230:233], v1 offset:22080
	ds_write_b128 v247, v[132:135] offset:17408
	s_waitcnt lgkmcnt(8)
	v_mfma_f32_32x32x16_bf16 v[80:95], v[234:237], v[116:119], v[80:95]
	v_add_f32_e32 v161, v161, v245
	v_cvt_pk_bf16_f32 v146, v100, v101
	v_cvt_pk_bf16_f32 v147, v102, v103
	ds_read_b128 v[234:237], v14 offset:8768
	ds_write_b128 v246, v[136:139] offset:8704
	s_waitcnt lgkmcnt(9)
	v_mfma_f32_32x32x16_bf16 v[80:95], v[2:5], v[120:123], v[80:95]
	v_cvt_pk_bf16_f32 v150, v104, v105
	v_cvt_pk_bf16_f32 v151, v106, v107
	ds_read_b128 v[2:5], v1 offset:26688
	ds_write_b128 v247, v[140:143] offset:26624
	s_waitcnt lgkmcnt(10)
	v_mfma_f32_32x32x16_bf16 v[80:95], v[248:251], v[124:127], v[80:95]
	v_cvt_pk_bf16_f32 v152, v108, v109
	v_cvt_pk_bf16_f32 v153, v110, v111
	s_cmp_ge_u32 s47, s23
	s_cbranch_scc1 .Lfa_noload_b
	s_lshl_b32 s48, s47, 17
	s_lshl_b32 s4, s47, 7
	s_add_u32 s48, s20, s48
	s_addc_u32 s49, s21, 0
	global_load_dwordx4 v[128:131], v240, s[48:49]
	s_add_u32 s4, s12, s4
	s_addc_u32 s25, s13, 0
	s_mov_b32 s5, s25
	global_load_dwordx4 v[132:135], v242, s[4:5]
	global_load_dwordx4 v[136:139], v241, s[48:49]
	global_load_dwordx4 v[140:143], v243, s[4:5]
	s_mov_b32 s5, 0
